# same as previous version plus 2 idle states so that 12 states separate the last state-update MFMA from the first VALU read of its result (Table 38)
# baseline (speedup 1.0000x reference)
.Ldnl1_go:
	v_cvt_pk_bf16_f32 v16, v0, v1
	v_cvt_pk_bf16_f32 v17, v2, v3
	v_cvt_pk_bf16_f32 v18, v4, v5
	v_cvt_pk_bf16_f32 v19, v6, v7
	ds_write2_b64 v159, v[16:17], v[18:19] offset1:2
	v_cvt_pk_bf16_f32 v16, v8, v9
	v_cvt_pk_bf16_f32 v17, v10, v11
	v_cvt_pk_bf16_f32 v18, v12, v13
	v_cvt_pk_bf16_f32 v19, v14, v15
	ds_write2_b64 v159, v[16:17], v[18:19] offset0:4 offset1:6
	s_waitcnt lgkmcnt(0)
	s_barrier
	ds_read_b128 v[44:47], v161 offset:41984
	ds_read_b128 v[40:43], v161 offset:42016
	ds_read_b128 v[36:39], v161 offset:42048
	ds_read_b128 v[32:35], v161 offset:42080
	ds_read_b64 v[52:53], v200
	ds_read_b64 v[54:55], v200 offset:2304
	ds_read_b128 v[206:209], v198
	ds_read_b128 v[226:229], v199
	ds_read_b128 v[16:19], v199 offset:4352
	ds_read_b128 v[210:213], v198 offset:64
	ds_read_b128 v[230:233], v199 offset:64
	ds_read_b128 v[20:23], v199 offset:4416
	ds_read_b128 v[214:217], v198 offset:128
	ds_read_b128 v[234:237], v199 offset:128
	ds_read_b128 v[24:27], v199 offset:4480
	v_readlane_b32 s20, v252, 27
	v_readlane_b32 s21, v252, 28
	s_add_u32 s20, s20, s8
	s_addc_u32 s21, s21, 0
	s_add_u32 s20, s20, 0x7489000
	s_addc_u32 s21, s21, 0
	global_store_dword v149, v0, s[20:21] nt
	global_store_dword v149, v1, s[20:21] offset:512 nt
	global_store_dword v149, v2, s[20:21] offset:1024 nt
	global_store_dword v149, v3, s[20:21] offset:1536 nt
	s_waitcnt lgkmcnt(6)
	v_mfma_f32_16x16x32_bf16 v[242:245], v[206:209], v[226:229], 0
	v_mfma_f32_16x16x32_bf16 v[246:249], v[206:209], v[16:19], 0
	ds_read_b128 v[222:225], v198 offset:192
	ds_read_b128 v[238:241], v199 offset:192
	ds_read_b128 v[28:31], v199 offset:4544
	s_add_u32 s20, s20, 0x1000
	s_addc_u32 s21, s21, 0
	global_store_dword v149, v4, s[20:21] nt
	global_store_dword v149, v5, s[20:21] offset:512 nt
	global_store_dword v149, v6, s[20:21] offset:1024 nt
	global_store_dword v149, v7, s[20:21] offset:1536 nt
	s_waitcnt lgkmcnt(6)
	v_mfma_f32_16x16x32_bf16 v[242:245], v[210:213], v[230:233], v[242:245]
	v_mfma_f32_16x16x32_bf16 v[246:249], v[210:213], v[20:23], v[246:249]
	s_add_u32 s20, s20, 0x1000
	s_addc_u32 s21, s21, 0
	global_store_dword v149, v8, s[20:21] nt
	global_store_dword v149, v9, s[20:21] offset:512 nt
	global_store_dword v149, v10, s[20:21] offset:1024 nt
	global_store_dword v149, v11, s[20:21] offset:1536 nt
	s_waitcnt lgkmcnt(3)
	v_mfma_f32_16x16x32_bf16 v[242:245], v[214:217], v[234:237], v[242:245]
	v_mfma_f32_16x16x32_bf16 v[246:249], v[214:217], v[24:27], v[246:249]
	s_add_u32 s20, s20, 0x1000
	s_addc_u32 s21, s21, 0
	global_store_dword v149, v12, s[20:21] nt
	global_store_dword v149, v13, s[20:21] offset:512 nt
	global_store_dword v149, v14, s[20:21] offset:1024 nt
	global_store_dword v149, v15, s[20:21] offset:1536 nt
	s_waitcnt lgkmcnt(0)
	v_mfma_f32_16x16x32_bf16 v[242:245], v[222:225], v[238:241], v[242:245]
	v_mfma_f32_16x16x32_bf16 v[246:249], v[222:225], v[28:31], v[246:249]
	v_lshlrev_b32_e32 v206, 16, v52
	v_and_b32_e32 v207, 0xffff0000, v52
	v_lshlrev_b32_e32 v208, 16, v53
	v_and_b32_e32 v209, 0xffff0000, v53
	v_lshlrev_b32_e32 v210, 16, v54
	v_and_b32_e32 v211, 0xffff0000, v54
	v_lshlrev_b32_e32 v212, 16, v55
	v_and_b32_e32 v213, 0xffff0000, v55
	s_nop 7
	s_nop 1
	v_pk_add_f32 v[206:207], v[206:207], v[242:243] neg_lo:[0,1] neg_hi:[0,1]
	v_pk_add_f32 v[208:209], v[208:209], v[244:245] neg_lo:[0,1] neg_hi:[0,1]
	v_pk_add_f32 v[210:211], v[210:211], v[246:247] neg_lo:[0,1] neg_hi:[0,1]
	v_pk_add_f32 v[212:213], v[212:213], v[248:249] neg_lo:[0,1] neg_hi:[0,1]
	v_cvt_pk_bf16_f32 v206, v206, v207
	v_cvt_pk_bf16_f32 v207, v208, v209
	v_cvt_pk_bf16_f32 v210, v210, v211
	v_cvt_pk_bf16_f32 v211, v212, v213
	ds_write_b64 v201, v[206:207]
	ds_write_b64 v201, v[210:211] offset:2304
	v_add_u32_e32 v176, v153, v171
	v_add_u32_e32 v178, v147, v155
	s_waitcnt lgkmcnt(0)
	s_barrier
	ds_read_b128 v[16:19], v178 offset:8704
	ds_read_b128 v[20:23], v178 offset:8736
	ds_read_b128 v[24:27], v178 offset:8768
	ds_read_b128 v[28:31], v178 offset:8800
	s_waitcnt vmcnt(25)
	v_pk_mul_f32 v[14:15], v[14:15], v[142:143] op_sel_hi:[1,0]
	v_pk_mul_f32 v[12:13], v[12:13], v[142:143] op_sel_hi:[1,0]
	v_pk_mul_f32 v[10:11], v[10:11], v[142:143] op_sel_hi:[1,0]
	v_pk_mul_f32 v[8:9], v[8:9], v[142:143] op_sel_hi:[1,0]
	v_pk_mul_f32 v[6:7], v[6:7], v[142:143] op_sel_hi:[1,0]
	v_pk_mul_f32 v[4:5], v[4:5], v[142:143] op_sel_hi:[1,0]
	v_pk_mul_f32 v[2:3], v[2:3], v[142:143] op_sel_hi:[1,0]
	v_pk_mul_f32 v[0:1], v[0:1], v[142:143] op_sel_hi:[1,0]
	s_waitcnt lgkmcnt(3)
	s_nop 0
	v_mfma_f32_32x32x16_bf16 v[0:15], v[44:47], v[16:19], v[0:15]
	s_waitcnt lgkmcnt(2)
	v_mfma_f32_32x32x16_bf16 v[0:15], v[40:43], v[20:23], v[0:15]
	s_waitcnt lgkmcnt(1)
	v_mfma_f32_32x32x16_bf16 v[0:15], v[36:39], v[24:27], v[0:15]
	s_waitcnt lgkmcnt(0)
	v_mfma_f32_32x32x16_bf16 v[0:15], v[32:35], v[28:31], v[0:15]
	s_waitcnt vmcnt(26)
	ds_write_b128 v146, v[94:97] offset:24576
	ds_write_b128 v148, v[56:59] offset:24576
	ds_write_b128 v150, v[60:63] offset:24576
	ds_write_b128 v152, v[72:75] offset:24576
	ds_write_b128 v154, v[76:79] offset:41984
	ds_write_b128 v156, v[86:89] offset:41984
	ds_write_b128 v158, v[90:93] offset:41984
	ds_write_b128 v160, v[106:109] offset:41984
	ds_write_b128 v154, v[110:113] offset:60416
	s_nop 1
	v_cvt_pk_bf16_f32 v16, v0, v1
	v_cvt_pk_bf16_f32 v17, v2, v3
	v_cvt_pk_bf16_f32 v18, v4, v5
	v_cvt_pk_bf16_f32 v19, v6, v7
	ds_write2_b64 v159, v[16:17], v[18:19] offset1:2
	v_cvt_pk_bf16_f32 v16, v8, v9
	v_cvt_pk_bf16_f32 v17, v10, v11
	v_cvt_pk_bf16_f32 v18, v12, v13
	v_cvt_pk_bf16_f32 v19, v14, v15
	ds_write2_b64 v159, v[16:17], v[18:19] offset0:4 offset1:6
	s_waitcnt lgkmcnt(0)
	s_barrier
	ds_read_b128 v[76:79], v161 offset:41984
	ds_read_b128 v[72:75], v161 offset:42016
	ds_read_b128 v[60:63], v161 offset:42048
	ds_read_b128 v[56:59], v161 offset:42080
	ds_read_b64 v[90:91], v200
	ds_read_b64 v[92:93], v200 offset:2304
	ds_read_b128 v[206:209], v198
	ds_read_b128 v[226:229], v199
	ds_read_b128 v[16:19], v199 offset:4352
	ds_read_b128 v[210:213], v198 offset:64
	ds_read_b128 v[230:233], v199 offset:64
	ds_read_b128 v[20:23], v199 offset:4416
	ds_read_b128 v[214:217], v198 offset:128
	ds_read_b128 v[234:237], v199 offset:128
	ds_read_b128 v[24:27], v199 offset:4480
	s_add_i32 s6, s15, -2
	s_cmp_eq_u32 s8, 0x2a0000
	s_cselect_b64 s[10:11], -1, 0
	s_and_b64 s[4:5], s[10:11], exec
	s_cselect_b32 s20, 0x80, s6
	s_add_i32 s6, s20, s14
	s_lshl_b64 s[22:23], s[6:7], 14
	s_add_u32 s100, s98, s22
	s_addc_u32 s101, s99, s23
	global_load_dwordx4 v[32:35], v189, s[100:101]
	global_load_dwordx4 v[36:39], v190, s[100:101]
	s_ashr_i32 s21, s20, 31
	global_load_dwordx4 v[40:43], v191, s[100:101]
	global_load_dwordx4 v[44:47], v192, s[100:101]
	s_waitcnt lgkmcnt(6)
	v_mfma_f32_16x16x32_bf16 v[242:245], v[206:209], v[226:229], 0
	v_mfma_f32_16x16x32_bf16 v[246:249], v[206:209], v[16:19], 0
	ds_read_b128 v[222:225], v198 offset:192
	ds_read_b128 v[238:241], v199 offset:192
	ds_read_b128 v[28:31], v199 offset:4544
	global_load_dwordx4 v[48:51], v193, s[100:101]
	global_load_dwordx4 v[52:55], v194, s[100:101]
	s_lshl_b64 s[4:5], s[20:21], 2
	s_add_u32 s4, s16, s4
	global_load_dwordx4 v[68:71], v195, s[100:101]
	s_waitcnt lgkmcnt(6)
	v_mfma_f32_16x16x32_bf16 v[242:245], v[210:213], v[230:233], v[242:245]
	v_mfma_f32_16x16x32_bf16 v[246:249], v[210:213], v[20:23], v[246:249]
	global_load_dwordx4 v[82:85], v196, s[100:101]
	s_addc_u32 s5, s17, s5
	global_load_dwordx4 v[64:67], v188, s[100:101]
	global_load_dword v177, v157, s[4:5]
	s_waitcnt lgkmcnt(3)
	v_mfma_f32_16x16x32_bf16 v[242:245], v[214:217], v[234:237], v[242:245]
	v_mfma_f32_16x16x32_bf16 v[246:249], v[214:217], v[24:27], v[246:249]
	s_waitcnt lgkmcnt(0)
	v_mfma_f32_16x16x32_bf16 v[242:245], v[222:225], v[238:241], v[242:245]
	v_mfma_f32_16x16x32_bf16 v[246:249], v[222:225], v[28:31], v[246:249]
	v_lshlrev_b32_e32 v206, 16, v90
	v_and_b32_e32 v207, 0xffff0000, v90
	v_lshlrev_b32_e32 v208, 16, v91
	v_and_b32_e32 v209, 0xffff0000, v91
	v_lshlrev_b32_e32 v210, 16, v92
	v_and_b32_e32 v211, 0xffff0000, v92
	v_lshlrev_b32_e32 v212, 16, v93
	v_and_b32_e32 v213, 0xffff0000, v93
	s_nop 7
	s_nop 1
	v_pk_add_f32 v[206:207], v[206:207], v[242:243] neg_lo:[0,1] neg_hi:[0,1]
	v_pk_add_f32 v[208:209], v[208:209], v[244:245] neg_lo:[0,1] neg_hi:[0,1]
	v_pk_add_f32 v[210:211], v[210:211], v[246:247] neg_lo:[0,1] neg_hi:[0,1]
	v_pk_add_f32 v[212:213], v[212:213], v[248:249] neg_lo:[0,1] neg_hi:[0,1]
	v_cvt_pk_bf16_f32 v206, v206, v207
	v_cvt_pk_bf16_f32 v207, v208, v209
	v_cvt_pk_bf16_f32 v210, v210, v211
	v_cvt_pk_bf16_f32 v211, v212, v213
	ds_write_b64 v201, v[206:207]
	ds_write_b64 v201, v[210:211] offset:2304
	s_waitcnt lgkmcnt(0)
	s_barrier
	s_nop 1
	ds_read_b128 v[16:19], v178 offset:8704
	ds_read_b128 v[20:23], v178 offset:8736
	ds_read_b128 v[24:27], v178 offset:8768
	ds_read_b128 v[28:31], v178 offset:8800
	v_pk_mul_f32 v[0:1], v[142:143], v[0:1] op_sel:[1,0]
	v_pk_mul_f32 v[14:15], v[142:143], v[14:15] op_sel:[1,0]
	v_pk_mul_f32 v[12:13], v[142:143], v[12:13] op_sel:[1,0]
	v_pk_mul_f32 v[10:11], v[142:143], v[10:11] op_sel:[1,0]
	v_pk_mul_f32 v[8:9], v[142:143], v[8:9] op_sel:[1,0]
	v_pk_mul_f32 v[6:7], v[142:143], v[6:7] op_sel:[1,0]
	v_pk_mul_f32 v[4:5], v[142:143], v[4:5] op_sel:[1,0]
	v_pk_mul_f32 v[2:3], v[142:143], v[2:3] op_sel:[1,0]
	s_waitcnt lgkmcnt(3)
	s_nop 0
	v_mfma_f32_32x32x16_bf16 v[0:15], v[76:79], v[16:19], v[0:15]
	s_waitcnt lgkmcnt(2)
	v_mfma_f32_32x32x16_bf16 v[0:15], v[72:75], v[20:23], v[0:15]
	s_waitcnt lgkmcnt(1)
	v_mfma_f32_32x32x16_bf16 v[0:15], v[60:63], v[24:27], v[0:15]
	s_waitcnt lgkmcnt(0)
	v_mfma_f32_32x32x16_bf16 v[0:15], v[56:59], v[28:31], v[0:15]
	s_waitcnt vmcnt(26)
	ds_write_b128 v146, v[130:133] offset:24576
	ds_write_b128 v148, v[98:101] offset:24576
	ds_write_b128 v150, v[102:105] offset:24576
	ds_write_b128 v152, v[114:117] offset:24576
	ds_write_b128 v154, v[118:121] offset:41984
	ds_write_b128 v156, v[122:125] offset:41984
	ds_write_b128 v158, v[126:129] offset:41984
	ds_write_b128 v160, v[134:137] offset:41984
	ds_write_b128 v154, v[138:141] offset:60416
	s_nop 1
	v_cvt_pk_bf16_f32 v16, v0, v1
	v_cvt_pk_bf16_f32 v17, v2, v3
	v_cvt_pk_bf16_f32 v18, v4, v5
	v_cvt_pk_bf16_f32 v19, v6, v7
	ds_write2_b64 v159, v[16:17], v[18:19] offset1:2
	v_cvt_pk_bf16_f32 v16, v8, v9
	v_cvt_pk_bf16_f32 v17, v10, v11
	v_cvt_pk_bf16_f32 v18, v12, v13
	v_cvt_pk_bf16_f32 v19, v14, v15
	ds_write2_b64 v159, v[16:17], v[18:19] offset0:4 offset1:6
	s_waitcnt lgkmcnt(0)
	s_barrier
	ds_read_b128 v[118:121], v161 offset:41984
	ds_read_b128 v[114:117], v161 offset:42016
	ds_read_b128 v[102:105], v161 offset:42048
	ds_read_b128 v[98:101], v161 offset:42080
	ds_read_b64 v[126:127], v200
	ds_read_b64 v[128:129], v200 offset:2304
	ds_read_b128 v[206:209], v198
	ds_read_b128 v[226:229], v199
	ds_read_b128 v[16:19], v199 offset:4352
	ds_read_b128 v[210:213], v198 offset:64
	ds_read_b128 v[230:233], v199 offset:64
	ds_read_b128 v[20:23], v199 offset:4416
	ds_read_b128 v[214:217], v198 offset:128
	ds_read_b128 v[234:237], v199 offset:128
	ds_read_b128 v[24:27], v199 offset:4480
	s_add_i32 s6, s15, -1
	s_and_b64 s[4:5], s[10:11], exec
	s_cselect_b32 s20, 0x80, s6
	s_add_i32 s6, s20, s14
	s_lshl_b64 s[22:23], s[6:7], 14
	s_add_u32 s100, s98, s22
	s_addc_u32 s101, s99, s23
	global_load_dwordx4 v[56:59], v189, s[100:101]
	global_load_dwordx4 v[60:63], v190, s[100:101]
	s_ashr_i32 s21, s20, 31
	global_load_dwordx4 v[72:75], v191, s[100:101]
	global_load_dwordx4 v[76:79], v192, s[100:101]
	s_waitcnt lgkmcnt(6)
	v_mfma_f32_16x16x32_bf16 v[242:245], v[206:209], v[226:229], 0
	v_mfma_f32_16x16x32_bf16 v[246:249], v[206:209], v[16:19], 0
	ds_read_b128 v[222:225], v198 offset:192
	ds_read_b128 v[238:241], v199 offset:192
	ds_read_b128 v[28:31], v199 offset:4544
	global_load_dwordx4 v[86:89], v193, s[100:101]
	global_load_dwordx4 v[90:93], v194, s[100:101]
	s_lshl_b64 s[4:5], s[20:21], 2
	s_add_u32 s4, s16, s4
	global_load_dwordx4 v[106:109], v195, s[100:101]
	s_waitcnt lgkmcnt(6)
	v_mfma_f32_16x16x32_bf16 v[242:245], v[210:213], v[230:233], v[242:245]
	v_mfma_f32_16x16x32_bf16 v[246:249], v[210:213], v[20:23], v[246:249]
	global_load_dwordx4 v[110:113], v196, s[100:101]
	s_addc_u32 s5, s17, s5
	global_load_dwordx4 v[94:97], v188, s[100:101]
	global_load_dword v143, v157, s[4:5]
	s_waitcnt lgkmcnt(3)
	v_mfma_f32_16x16x32_bf16 v[242:245], v[214:217], v[234:237], v[242:245]
	v_mfma_f32_16x16x32_bf16 v[246:249], v[214:217], v[24:27], v[246:249]
	s_waitcnt lgkmcnt(0)
	v_mfma_f32_16x16x32_bf16 v[242:245], v[222:225], v[238:241], v[242:245]
	v_mfma_f32_16x16x32_bf16 v[246:249], v[222:225], v[28:31], v[246:249]
	v_lshlrev_b32_e32 v206, 16, v126
	v_and_b32_e32 v207, 0xffff0000, v126
	v_lshlrev_b32_e32 v208, 16, v127
	v_and_b32_e32 v209, 0xffff0000, v127
	v_lshlrev_b32_e32 v210, 16, v128
	v_and_b32_e32 v211, 0xffff0000, v128
	v_lshlrev_b32_e32 v212, 16, v129
	v_and_b32_e32 v213, 0xffff0000, v129
	s_nop 7
	s_nop 1
	v_pk_add_f32 v[206:207], v[206:207], v[242:243] neg_lo:[0,1] neg_hi:[0,1]
	v_pk_add_f32 v[208:209], v[208:209], v[244:245] neg_lo:[0,1] neg_hi:[0,1]
	v_pk_add_f32 v[210:211], v[210:211], v[246:247] neg_lo:[0,1] neg_hi:[0,1]
	v_pk_add_f32 v[212:213], v[212:213], v[248:249] neg_lo:[0,1] neg_hi:[0,1]
	v_cvt_pk_bf16_f32 v206, v206, v207
	v_cvt_pk_bf16_f32 v207, v208, v209
	v_cvt_pk_bf16_f32 v210, v210, v211
	v_cvt_pk_bf16_f32 v211, v212, v213
	ds_write_b64 v201, v[206:207]
	ds_write_b64 v201, v[210:211] offset:2304
	s_branch .LBB0_477
